# removed two compiler-inserted vmcnt(0) drains before LDS reads in attention loop and delta-scan chunk loop (LDS-DMA prefetch stays in flight)
# baseline (speedup 1.0000x reference)
.LBB0_204:
	s_lshl_b32 s40, s7, 13
	s_add_i32 s41, s40, 0xffffe000
	s_cmp_gt_i32 s7, 0
	s_cselect_b32 s41, s41, 0x4000
	s_add_i32 s41, s41, 0
	v_add_u32_e32 v36, s41, v136
	v_lshl_add_u64 v[34:35], s[38:39], 0, v[116:117]
	v_readfirstlane_b32 s52, v36
	v_lshl_add_u64 v[34:35], v[34:35], 0, v[130:131]
	s_mov_b32 m0, s52
	v_add_u32_e32 v36, 0x6000, v36
	global_load_lds_dwordx4 v[34:35], off
	v_lshl_add_u64 v[34:35], s[36:37], 0, v[116:117]
	v_mov_b32_e32 v119, v131
	v_readfirstlane_b32 s52, v36
	v_lshl_add_u64 v[34:35], v[34:35], 0, v[118:119]
	s_mov_b32 m0, s52
	v_add_u32_e32 v36, s41, v138
	global_load_lds_dwordx4 v[34:35], off
	v_lshl_add_u64 v[34:35], s[38:39], 0, v[120:121]
	v_mov_b32_e32 v115, v131
	v_readfirstlane_b32 s38, v36
	v_lshl_add_u64 v[34:35], v[34:35], 0, v[114:115]
	s_mov_b32 m0, s38
	v_add_u32_e32 v36, 0x6000, v36
	global_load_lds_dwordx4 v[34:35], off
	v_lshl_add_u64 v[34:35], s[36:37], 0, v[120:121]
	v_mov_b32_e32 v123, v131
	v_readfirstlane_b32 s36, v36
	v_lshl_add_u64 v[34:35], v[34:35], 0, v[122:123]
	s_mov_b32 m0, s36
	v_add_u32_e32 v42, s40, v137
	global_load_lds_dwordx4 v[34:35], off
	v_add_u32_e32 v38, v42, v139
	ds_read_b128 v[34:37], v38
	v_add_u32_e32 v43, v42, v129
	ds_read_b128 v[82:85], v43 offset:4096
	ds_read_b128 v[38:41], v38 offset:4096
	s_waitcnt lgkmcnt(0)
	v_mfma_f32_32x32x16_bf16 v[50:65], v[34:37], v[78:81], 0
	ds_read_b128 v[34:37], v43
	v_add_u32_e32 v44, v42, v128
	ds_read_b128 v[86:89], v44 offset:4096
	v_add_u32_e32 v42, v42, v127
	s_add_i32 s36, s7, 1
	s_cmp_lg_u32 s7, 2
	s_cselect_b32 s7, s36, 0
	s_waitcnt lgkmcnt(0)
	v_mfma_f32_32x32x16_bf16 v[50:65], v[34:37], v[74:77], v[50:65]
	ds_read_b128 v[34:37], v44
	s_add_u32 s10, s10, 0x4000
	s_addc_u32 s11, s11, 0
	s_add_i32 s51, s51, 64
	s_add_i32 s43, s43, 1
	s_cmp_eq_u32 s48, s10
	s_waitcnt lgkmcnt(0)
	v_mfma_f32_32x32x16_bf16 v[50:65], v[34:37], v[70:73], v[50:65]
	ds_read_b128 v[34:37], v42
	ds_read_b128 v[90:93], v42 offset:4096
	s_waitcnt lgkmcnt(0)
	v_mfma_f32_32x32x16_bf16 v[50:65], v[34:37], v[66:69], v[50:65]
	v_mfma_f32_32x32x16_bf16 v[34:49], v[38:41], v[78:81], 0
	s_nop 10
	v_max_f32_e32 v98, v51, v51
	v_max_f32_e32 v99, v50, v50
	v_max_f32_e32 v98, v99, v98
	v_max3_f32 v98, v98, v52, v53
	v_max3_f32 v98, v98, v54, v55
	v_max3_f32 v98, v98, v56, v57
	v_max3_f32 v98, v98, v58, v59
	v_mfma_f32_32x32x16_bf16 v[34:49], v[82:85], v[74:77], v[34:49]
	v_max3_f32 v98, v98, v60, v61
	v_max3_f32 v98, v98, v62, v63
	v_max3_f32 v98, v98, v64, v65
	v_and_b32_e32 v99, 64, v198
	v_add_u32_e32 v99, 64, v99
	v_add_u32_e32 v82, s40, v124
	v_add_u32_e32 v84, v82, v125
	v_mfma_f32_32x32x16_bf16 v[34:49], v[86:89], v[70:73], v[34:49]
	v_add_u32_e32 v100, v82, v126
	v_mfma_f32_32x32x16_bf16 v[34:49], v[90:93], v[66:69], v[34:49]
	ds_read_b64_tr_b16 v[102:103], v84 offset:24576
	ds_read_b64_tr_b16 v[104:105], v84 offset:25600
	ds_read_b64_tr_b16 v[94:95], v84 offset:26624
	ds_read_b64_tr_b16 v[96:97], v84 offset:27648
	ds_read_b64_tr_b16 v[106:107], v100 offset:24576
	ds_read_b64_tr_b16 v[108:109], v100 offset:25600
	ds_read_b64_tr_b16 v[90:91], v100 offset:26624
	ds_read_b64_tr_b16 v[92:93], v100 offset:27648
	ds_read_b64_tr_b16 v[86:87], v84 offset:28672
	ds_read_b64_tr_b16 v[88:89], v84 offset:29696
	ds_read_b64_tr_b16 v[82:83], v84 offset:30720
	ds_read_b64_tr_b16 v[84:85], v84 offset:31744
	v_max3_f32 v98, v98, v34, v35
	v_max3_f32 v98, v98, v36, v37
	v_max3_f32 v98, v98, v38, v39
	v_max3_f32 v98, v98, v40, v41
	v_max3_f32 v98, v98, v42, v43
	v_max3_f32 v98, v98, v44, v45
	v_max3_f32 v98, v98, v46, v47
	v_max3_f32 v115, v98, v48, v49
	v_xor_b32_e32 v98, 32, v198
	v_cmp_lt_i32_e32 vcc, v98, v99
	s_nop 1
	v_cndmask_b32_e32 v98, v198, v98, vcc
	v_lshlrev_b32_e32 v206, 2, v98
	ds_bpermute_b32 v119, v206, v115
	ds_read_b64_tr_b16 v[110:111], v100 offset:28672
	ds_read_b64_tr_b16 v[112:113], v100 offset:29696
	ds_read_b64_tr_b16 v[98:99], v100 offset:30720
	ds_read_b64_tr_b16 v[100:101], v100 offset:31744
	s_waitcnt lgkmcnt(4)
	v_max_f32_e32 v119, v119, v119
	v_max_f32_e32 v115, v115, v119
	v_mul_f32_e32 v115, 0x3e38aa3b, v115
	v_max_f32_e32 v119, v141, v141
	v_max_f32_e32 v119, v119, v115
	v_fma_f32 v50, v50, s18, -v119
	v_exp_f32_e32 v115, v50
	v_fma_f32 v50, v51, s18, -v119
	v_exp_f32_e32 v51, v50
	v_fma_f32 v52, v52, s18, -v119
	v_exp_f32_e32 v52, v52
	v_fma_f32 v53, v53, s18, -v119
	v_exp_f32_e32 v53, v53
	v_fma_f32 v54, v54, s18, -v119
	v_add_f32_e32 v123, 0, v115
	v_exp_f32_e32 v54, v54
	v_fma_f32 v55, v55, s18, -v119
	v_add_f32_e32 v123, v51, v123
	v_exp_f32_e32 v55, v55
	v_fma_f32 v56, v56, s18, -v119
	v_add_f32_e32 v123, v52, v123
	v_exp_f32_e32 v56, v56
	v_fma_f32 v57, v57, s18, -v119
	v_add_f32_e32 v123, v53, v123
	v_exp_f32_e32 v57, v57
	v_fma_f32 v58, v58, s18, -v119
	v_add_f32_e32 v123, v54, v123
	v_exp_f32_e32 v58, v58
	v_fma_f32 v59, v59, s18, -v119
	v_add_f32_e32 v123, v55, v123
	v_exp_f32_e32 v59, v59
	v_fma_f32 v60, v60, s18, -v119
	v_add_f32_e32 v123, v56, v123
	v_exp_f32_e32 v60, v60
	v_fma_f32 v61, v61, s18, -v119
	v_add_f32_e32 v123, v57, v123
	v_exp_f32_e32 v61, v61
	v_fma_f32 v62, v62, s18, -v119
	v_add_f32_e32 v123, v58, v123
	v_exp_f32_e32 v62, v62
	v_fma_f32 v63, v63, s18, -v119
	v_add_f32_e32 v123, v59, v123
	v_exp_f32_e32 v63, v63
	v_fma_f32 v64, v64, s18, -v119
	v_add_f32_e32 v123, v60, v123
	v_exp_f32_e32 v64, v64
	v_fma_f32 v65, v65, s18, -v119
	v_add_f32_e32 v123, v61, v123
	v_exp_f32_e32 v65, v65
	v_fma_f32 v34, v34, s18, -v119
	v_sub_f32_e32 v50, v141, v119
	v_add_f32_e32 v123, v62, v123
	v_exp_f32_e32 v141, v34
	v_fma_f32 v34, v35, s18, -v119
	v_add_f32_e32 v123, v63, v123
	v_exp_f32_e32 v142, v34
	v_fma_f32 v35, v36, s18, -v119
	v_add_f32_e32 v34, v64, v123
	v_exp_f32_e32 v123, v35
	v_fma_f32 v35, v37, s18, -v119
	v_add_f32_e32 v34, v65, v34
	v_exp_f32_e32 v143, v35
	v_fma_f32 v35, v38, s18, -v119
	v_add_f32_e32 v34, v141, v34
	v_exp_f32_e32 v38, v35
	v_fma_f32 v35, v39, s18, -v119
	v_add_f32_e32 v34, v142, v34
	v_exp_f32_e32 v39, v35
	v_exp_f32_e32 v50, v50
	v_add_f32_e32 v34, v123, v34
	v_add_f32_e32 v34, v143, v34
	v_add_f32_e32 v34, v38, v34
	v_add_f32_e32 v144, v39, v34
	v_fma_f32 v34, v40, s18, -v119
	v_exp_f32_e32 v40, v34
	v_pk_mul_f32 v[32:33], v[32:33], v[50:51] op_sel_hi:[1,0]
	v_pk_mul_f32 v[30:31], v[30:31], v[50:51] op_sel_hi:[1,0]
	v_pk_mul_f32 v[28:29], v[28:29], v[50:51] op_sel_hi:[1,0]
	v_pk_mul_f32 v[26:27], v[26:27], v[50:51] op_sel_hi:[1,0]
	v_pk_mul_f32 v[24:25], v[24:25], v[50:51] op_sel_hi:[1,0]
	v_pk_mul_f32 v[22:23], v[22:23], v[50:51] op_sel_hi:[1,0]
	v_pk_mul_f32 v[20:21], v[20:21], v[50:51] op_sel_hi:[1,0]
	v_pk_mul_f32 v[18:19], v[18:19], v[50:51] op_sel_hi:[1,0]
	v_pk_mul_f32 v[16:17], v[16:17], v[50:51] op_sel_hi:[1,0]
	v_cvt_pk_bf16_f32 v34, v115, v51
	v_cvt_pk_bf16_f32 v35, v52, v53
	v_cvt_pk_bf16_f32 v36, v54, v55
	v_cvt_pk_bf16_f32 v37, v56, v57
	v_pk_mul_f32 v[14:15], v[14:15], v[50:51] op_sel_hi:[1,0]
	v_pk_mul_f32 v[12:13], v[12:13], v[50:51] op_sel_hi:[1,0]
	v_pk_mul_f32 v[10:11], v[10:11], v[50:51] op_sel_hi:[1,0]
	v_pk_mul_f32 v[8:9], v[8:9], v[50:51] op_sel_hi:[1,0]
	v_pk_mul_f32 v[6:7], v[6:7], v[50:51] op_sel_hi:[1,0]
	v_pk_mul_f32 v[4:5], v[4:5], v[50:51] op_sel_hi:[1,0]
	v_pk_mul_f32 v[2:3], v[2:3], v[50:51] op_sel_hi:[1,0]
	v_mfma_f32_32x32x16_bf16 v[18:33], v[102:105], v[34:37], v[18:33]
	v_fma_f32 v42, v42, s18, -v119
	v_exp_f32_e32 v42, v42
	v_fma_f32 v43, v43, s18, -v119
	v_exp_f32_e32 v43, v43
	v_fma_f32 v44, v44, s18, -v119
	v_add_f32_e32 v51, v40, v144
	v_exp_f32_e32 v44, v44
	v_mfma_f32_32x32x16_bf16 v[2:17], v[106:109], v[34:37], v[2:17]
	v_fma_f32 v34, v41, s18, -v119
	v_exp_f32_e32 v41, v34
	v_cvt_pk_bf16_f32 v34, v58, v59
	v_cvt_pk_bf16_f32 v35, v60, v61
	v_cvt_pk_bf16_f32 v36, v62, v63
	v_cvt_pk_bf16_f32 v37, v64, v65
	v_add_f32_e32 v51, v41, v51
	s_nop 0
	v_mfma_f32_32x32x16_bf16 v[18:33], v[94:97], v[34:37], v[18:33]
	v_mfma_f32_32x32x16_bf16 v[2:17], v[90:93], v[34:37], v[2:17]
	v_add_f32_e32 v34, v42, v51
	v_add_f32_e32 v34, v43, v34
	v_add_f32_e32 v51, v44, v34
	v_cvt_pk_bf16_f32 v34, v141, v142
	v_cvt_pk_bf16_f32 v35, v123, v143
	v_cvt_pk_bf16_f32 v36, v38, v39
	v_cvt_pk_bf16_f32 v37, v40, v41
	v_fma_f32 v38, v45, s18, -v119
	v_fma_f32 v39, v46, s18, -v119
	v_mfma_f32_32x32x16_bf16 v[18:33], v[86:89], v[34:37], v[18:33]
	v_fma_f32 v40, v47, s18, -v119
	v_fma_f32 v41, v48, s18, -v119
	v_exp_f32_e32 v38, v38
	v_exp_f32_e32 v39, v39
	v_exp_f32_e32 v40, v40
	v_exp_f32_e32 v41, v41
	s_waitcnt lgkmcnt(2)
	v_mfma_f32_32x32x16_bf16 v[2:17], v[110:113], v[34:37], v[2:17]
	v_fma_f32 v34, v49, s18, -v119
	v_exp_f32_e32 v45, v34
	v_cvt_pk_bf16_f32 v34, v42, v43
	v_cvt_pk_bf16_f32 v35, v44, v38
	v_cvt_pk_bf16_f32 v36, v39, v40
	v_cvt_pk_bf16_f32 v37, v41, v45
	v_add_f32_e32 v38, v38, v51
	v_add_f32_e32 v38, v39, v38
	v_mfma_f32_32x32x16_bf16 v[18:33], v[82:85], v[34:37], v[18:33]
	v_add_f32_e32 v38, v40, v38
	v_add_f32_e32 v38, v41, v38
	v_add_f32_e32 v115, v45, v38
	v_fmac_f32_e32 v115, v140, v50
	s_waitcnt lgkmcnt(0)
	v_mfma_f32_32x32x16_bf16 v[2:17], v[98:101], v[34:37], v[2:17]
	s_cbranch_scc1 .LBB0_206
	v_mov_b32_e32 v140, v115
	v_mov_b32_e32 v141, v119
	s_branch .LBB0_200

.LBB0_227:
	v_and_b32_sdwa v2, v61, v1 dst_sel:DWORD dst_unused:UNUSED_PAD src0_sel:WORD_1 src1_sel:DWORD
	v_and_b32_sdwa v3, v60, v1 dst_sel:DWORD dst_unused:UNUSED_PAD src0_sel:WORD_1 src1_sel:DWORD
	v_add3_u32 v2, v61, v2, s26
	v_add3_u32 v78, v60, v3, s26
	v_and_b32_e32 v3, 0xffff0000, v2
	v_and_b32_e32 v2, 0xffff0000, v78
	v_pk_add_f32 v[6:7], v[60:61], v[2:3] neg_lo:[0,1] neg_hi:[0,1]
	v_and_b32_sdwa v2, v63, v1 dst_sel:DWORD dst_unused:UNUSED_PAD src0_sel:WORD_1 src1_sel:DWORD
	v_and_b32_sdwa v4, v62, v1 dst_sel:DWORD dst_unused:UNUSED_PAD src0_sel:WORD_1 src1_sel:DWORD
	v_add3_u32 v2, v63, v2, s26
	v_add3_u32 v79, v62, v4, s26
	v_and_b32_e32 v5, 0xffff0000, v2
	v_and_b32_e32 v4, 0xffff0000, v79
	v_pk_add_f32 v[8:9], v[62:63], v[4:5] neg_lo:[0,1] neg_hi:[0,1]
	v_and_b32_sdwa v2, v59, v1 dst_sel:DWORD dst_unused:UNUSED_PAD src0_sel:WORD_1 src1_sel:DWORD
	v_and_b32_sdwa v4, v58, v1 dst_sel:DWORD dst_unused:UNUSED_PAD src0_sel:WORD_1 src1_sel:DWORD
	v_add3_u32 v2, v59, v2, s26
	v_add3_u32 v4, v58, v4, s26
	v_and_b32_e32 v11, 0xffff0000, v2
	v_and_b32_e32 v10, 0xffff0000, v4
	v_and_b32_sdwa v2, v65, v1 dst_sel:DWORD dst_unused:UNUSED_PAD src0_sel:WORD_1 src1_sel:DWORD
	v_pk_add_f32 v[12:13], v[58:59], v[10:11] neg_lo:[0,1] neg_hi:[0,1]
	v_and_b32_sdwa v10, v64, v1 dst_sel:DWORD dst_unused:UNUSED_PAD src0_sel:WORD_1 src1_sel:DWORD
	v_add3_u32 v2, v65, v2, s26
	v_add3_u32 v10, v64, v10, s26
	v_and_b32_e32 v15, 0xffff0000, v2
	v_and_b32_e32 v14, 0xffff0000, v10
	v_or_b32_sdwa v2, v3, v78 dst_sel:DWORD dst_unused:UNUSED_PAD src0_sel:DWORD src1_sel:WORD_1
	v_or_b32_sdwa v3, v11, v4 dst_sel:DWORD dst_unused:UNUSED_PAD src0_sel:DWORD src1_sel:WORD_1
	v_or_b32_sdwa v4, v5, v79 dst_sel:DWORD dst_unused:UNUSED_PAD src0_sel:DWORD src1_sel:WORD_1
	v_or_b32_sdwa v5, v15, v10 dst_sel:DWORD dst_unused:UNUSED_PAD src0_sel:DWORD src1_sel:WORD_1
	v_and_b32_sdwa v10, v67, v1 dst_sel:DWORD dst_unused:UNUSED_PAD src0_sel:WORD_1 src1_sel:DWORD
	v_and_b32_sdwa v11, v66, v1 dst_sel:DWORD dst_unused:UNUSED_PAD src0_sel:WORD_1 src1_sel:DWORD
	v_pk_add_f32 v[16:17], v[64:65], v[14:15] neg_lo:[0,1] neg_hi:[0,1]
	v_add3_u32 v10, v67, v10, s26
	v_add3_u32 v14, v66, v11, s26
	v_and_b32_e32 v11, 0xffff0000, v10
	v_and_b32_e32 v10, 0xffff0000, v14
	v_pk_add_f32 v[78:79], v[66:67], v[10:11] neg_lo:[0,1] neg_hi:[0,1]
	v_and_b32_sdwa v10, v71, v1 dst_sel:DWORD dst_unused:UNUSED_PAD src0_sel:WORD_1 src1_sel:DWORD
	v_add3_u32 v10, v71, v10, s26
	v_cvt_pk_bf16_f32 v6, v6, v7
	v_cvt_pk_bf16_f32 v7, v12, v13
	v_and_b32_e32 v13, 0xffff0000, v10
	v_and_b32_sdwa v10, v69, v1 dst_sel:DWORD dst_unused:UNUSED_PAD src0_sel:WORD_1 src1_sel:DWORD
	s_and_b32 s6, s40, 0x8000
	v_add3_u32 v10, v69, v10, s26
	v_and_b32_e32 v101, 0xffff0000, v10
	v_and_b32_sdwa v10, v73, v1 dst_sel:DWORD dst_unused:UNUSED_PAD src0_sel:WORD_1 src1_sel:DWORD
	v_add_u32_e32 v149, s6, v112
	v_and_b32_sdwa v12, v70, v1 dst_sel:DWORD dst_unused:UNUSED_PAD src0_sel:WORD_1 src1_sel:DWORD
	v_and_b32_sdwa v15, v72, v1 dst_sel:DWORD dst_unused:UNUSED_PAD src0_sel:WORD_1 src1_sel:DWORD
	v_add3_u32 v10, v73, v10, s26
	v_add_u32_e32 v184, v149, v23
	v_add_u32_e32 v185, v149, v95
	v_cvt_pk_bf16_f32 v8, v8, v9
	v_cvt_pk_bf16_f32 v9, v16, v17
	v_add3_u32 v102, v70, v12, s26
	v_add3_u32 v146, v72, v15, s26
	v_and_b32_e32 v145, 0xffff0000, v10
	v_or_b32_sdwa v10, v11, v14 dst_sel:DWORD dst_unused:UNUSED_PAD src0_sel:DWORD src1_sel:WORD_1
	ds_read2st64_b64 v[14:17], v184 offset1:4
	ds_read2st64_b64 v[96:99], v185 offset1:4
	v_and_b32_e32 v12, 0xffff0000, v102
	v_pk_add_f32 v[108:109], v[70:71], v[12:13] neg_lo:[0,1] neg_hi:[0,1]
	v_and_b32_sdwa v12, v68, v1 dst_sel:DWORD dst_unused:UNUSED_PAD src0_sel:WORD_1 src1_sel:DWORD
	v_add3_u32 v12, v68, v12, s26
	v_and_b32_e32 v100, 0xffff0000, v12
	v_pk_add_f32 v[162:163], v[68:69], v[100:101] neg_lo:[0,1] neg_hi:[0,1]
	v_or_b32_sdwa v11, v101, v12 dst_sel:DWORD dst_unused:UNUSED_PAD src0_sel:DWORD src1_sel:WORD_1
	v_or_b32_sdwa v12, v13, v102 dst_sel:DWORD dst_unused:UNUSED_PAD src0_sel:DWORD src1_sel:WORD_1
	s_waitcnt lgkmcnt(0)
	v_mov_b32_e32 v100, v14
	v_mov_b32_e32 v101, v15
	v_mov_b32_e32 v102, v96
	v_mov_b32_e32 v103, v97
	v_mov_b32_e32 v96, v16
	v_mov_b32_e32 v97, v17
	v_and_b32_e32 v144, 0xffff0000, v146
	v_pk_add_f32 v[170:171], v[72:73], v[144:145] neg_lo:[0,1] neg_hi:[0,1]
	ds_read2st64_b64 v[104:107], v184 offset0:16 offset1:20
	v_or_b32_sdwa v13, v145, v146 dst_sel:DWORD dst_unused:UNUSED_PAD src0_sel:DWORD src1_sel:WORD_1
	ds_read2st64_b64 v[144:147], v185 offset0:16 offset1:20
	v_mfma_f32_16x16x32_bf16 v[154:157], v[100:103], v[2:5], 0
	v_add_u32_e32 v186, v149, v110
	v_add_u32_e32 v187, v149, v111
	s_waitcnt lgkmcnt(1)
	v_mov_b32_e32 v150, v104
	v_mfma_f32_16x16x32_bf16 v[14:17], v[96:99], v[2:5], 0
	v_mov_b32_e32 v151, v105
	s_waitcnt lgkmcnt(0)
	v_mov_b32_e32 v152, v144
	v_mov_b32_e32 v153, v145
	v_mfma_f32_16x16x32_bf16 v[100:103], v[100:103], v[6:9], v[154:157]
	ds_read2st64_b64 v[158:161], v187 offset1:4
	v_mov_b32_e32 v144, v106
	v_mov_b32_e32 v145, v107
	ds_read2st64_b64 v[154:157], v186 offset1:4
	v_mfma_f32_16x16x32_bf16 v[14:17], v[96:99], v[6:9], v[14:17]
	v_cvt_pk_bf16_f32 v149, v162, v163
	ds_read2st64_b64 v[162:165], v186 offset0:16 offset1:20
	ds_read2st64_b64 v[166:169], v187 offset0:16 offset1:20
	v_mfma_f32_16x16x32_bf16 v[100:103], v[150:153], v[2:5], v[100:103]
	s_waitcnt lgkmcnt(2)
	v_mov_b32_e32 v152, v154
	v_mov_b32_e32 v153, v155
	v_mov_b32_e32 v154, v158
	v_mov_b32_e32 v155, v159
	v_mov_b32_e32 v158, v156
	v_mov_b32_e32 v159, v157
	v_mfma_f32_16x16x32_bf16 v[14:17], v[144:147], v[2:5], v[14:17]
	ds_read2st64_b64 v[96:99], v184 offset0:8 offset1:12
	ds_read2st64_b64 v[104:107], v185 offset0:8 offset1:12
	v_cvt_pk_bf16_f32 v148, v78, v79
	v_mfma_f32_16x16x32_bf16 v[14:17], v[158:161], v[10:13], v[14:17]
	v_cvt_pk_bf16_f32 v150, v108, v109
	v_cvt_pk_bf16_f32 v151, v170, v171
	s_waitcnt lgkmcnt(2)
	v_mov_b32_e32 v172, v166
	v_mov_b32_e32 v173, v167
	v_mov_b32_e32 v166, v164
	v_mov_b32_e32 v167, v165
	v_mfma_f32_16x16x32_bf16 v[100:103], v[152:155], v[10:13], v[100:103]
	s_waitcnt lgkmcnt(1)
	v_mov_b32_e32 v144, v96
	v_mov_b32_e32 v145, v97
	s_waitcnt lgkmcnt(0)
	v_mov_b32_e32 v146, v104
	v_mfma_f32_16x16x32_bf16 v[14:17], v[158:161], v[148:151], v[14:17]
	v_mov_b32_e32 v147, v105
	v_mov_b32_e32 v104, v98
	v_mov_b32_e32 v105, v99
	v_mov_b32_e32 v170, v162
	v_mov_b32_e32 v171, v163
	v_mfma_f32_16x16x32_bf16 v[100:103], v[152:155], v[148:151], v[100:103]
	ds_read2st64_b64 v[152:155], v184 offset0:24 offset1:28
	s_add_i32 s44, s44, s39
	s_lshl_b32 s6, s44, 3
	v_mfma_f32_16x16x32_bf16 v[156:159], v[166:169], v[10:13], v[14:17]
	s_or_b32 s6, s6, s42
	s_waitcnt lgkmcnt(0)
	v_mov_b32_e32 v160, v152
	v_mov_b32_e32 v161, v153
	ds_read2st64_b64 v[14:17], v185 offset0:24 offset1:28
	v_mfma_f32_16x16x32_bf16 v[164:167], v[144:147], v[2:5], 0
	s_ashr_i32 s7, s6, 31
	s_add_i32 s41, s41, -1
	s_add_i32 s40, s40, 0x8000
	v_mfma_f32_16x16x32_bf16 v[96:99], v[104:107], v[2:5], 0
	s_waitcnt lgkmcnt(0)
	v_mov_b32_e32 v162, v14
	v_mov_b32_e32 v163, v15
	v_mov_b32_e32 v14, v154
	v_mfma_f32_16x16x32_bf16 v[100:103], v[170:173], v[10:13], v[100:103]
	v_mov_b32_e32 v15, v155
	s_cmp_eq_u32 s43, s38
	v_mfma_f32_16x16x32_bf16 v[144:147], v[144:147], v[6:9], v[164:167]
	s_nop 2
	ds_read2st64_b64 v[164:167], v186 offset0:8 offset1:12
	ds_read2st64_b64 v[168:171], v187 offset0:8 offset1:12
	ds_read2st64_b64 v[172:175], v186 offset0:24 offset1:28
	ds_read2st64_b64 v[176:179], v187 offset0:24 offset1:28
	v_sub_f32_e32 v78, v138, v100
	v_mfma_f32_16x16x32_bf16 v[6:9], v[104:107], v[6:9], v[96:99]
	v_sub_f32_e32 v102, v140, v102
	s_waitcnt lgkmcnt(1)
	v_mov_b32_e32 v180, v172
	v_mov_b32_e32 v181, v173
	v_mfma_f32_16x16x32_bf16 v[144:147], v[160:163], v[2:5], v[144:147]
	v_mov_b32_e32 v160, v164
	v_mov_b32_e32 v161, v165
	v_mov_b32_e32 v162, v168
	v_mov_b32_e32 v163, v169
	v_mov_b32_e32 v168, v166
	v_mov_b32_e32 v169, v167
	v_mfma_f32_16x16x32_bf16 v[2:5], v[14:17], v[2:5], v[6:9]
	s_waitcnt lgkmcnt(0)
	v_mov_b32_e32 v182, v176
	v_mov_b32_e32 v183, v177
	v_mov_b32_e32 v176, v174
	v_mfma_f32_16x16x32_bf16 v[144:147], v[160:163], v[10:13], v[144:147]
	v_mov_b32_e32 v177, v175
	v_sub_f32_e32 v79, v139, v101
	v_and_b32_sdwa v7, v78, v1 dst_sel:DWORD dst_unused:UNUSED_PAD src0_sel:WORD_1 src1_sel:DWORD
	v_mfma_f32_16x16x32_bf16 v[2:5], v[168:171], v[10:13], v[2:5]
	v_sub_f32_e32 v103, v141, v103
	v_add3_u32 v14, v78, v7, s26
	v_and_b32_sdwa v7, v102, v1 dst_sel:DWORD dst_unused:UNUSED_PAD src0_sel:WORD_1 src1_sel:DWORD
	v_mfma_f32_16x16x32_bf16 v[144:147], v[160:163], v[148:151], v[144:147]
	v_and_b32_sdwa v8, v79, v1 dst_sel:DWORD dst_unused:UNUSED_PAD src0_sel:WORD_1 src1_sel:DWORD
	v_and_b32_sdwa v6, v103, v1 dst_sel:DWORD dst_unused:UNUSED_PAD src0_sel:WORD_1 src1_sel:DWORD
	v_add3_u32 v15, v102, v7, s26
	v_mfma_f32_16x16x32_bf16 v[2:5], v[168:171], v[148:151], v[2:5]
	v_add3_u32 v7, v79, v8, s26
	v_and_b32_e32 v7, 0xffff0000, v7
	v_sub_f32_e32 v106, v18, v156
	v_mfma_f32_16x16x32_bf16 v[144:147], v[180:183], v[10:13], v[144:147]
	v_sub_f32_e32 v99, v21, v159
	v_sub_f32_e32 v98, v20, v158
	v_sub_f32_e32 v107, v19, v157
	v_mfma_f32_16x16x32_bf16 v[2:5], v[176:179], v[10:13], v[2:5]
	v_add3_u32 v11, v103, v6, s26
	v_and_b32_e32 v6, 0xffff0000, v14
	v_pk_add_f32 v[8:9], v[78:79], v[6:7] neg_lo:[0,1] neg_hi:[0,1]
	v_and_b32_e32 v10, 0xffff0000, v15
	v_and_b32_e32 v11, 0xffff0000, v11
	v_or_b32_sdwa v14, v14, v7 dst_sel:DWORD dst_unused:UNUSED_PAD src0_sel:WORD_1 src1_sel:DWORD
	v_and_b32_sdwa v7, v106, v1 dst_sel:DWORD dst_unused:UNUSED_PAD src0_sel:WORD_1 src1_sel:DWORD
	v_pk_add_f32 v[12:13], v[102:103], v[10:11] neg_lo:[0,1] neg_hi:[0,1]
	v_and_b32_sdwa v6, v99, v1 dst_sel:DWORD dst_unused:UNUSED_PAD src0_sel:WORD_1 src1_sel:DWORD
	v_add3_u32 v18, v106, v7, s26
	v_and_b32_sdwa v7, v98, v1 dst_sel:DWORD dst_unused:UNUSED_PAD src0_sel:WORD_1 src1_sel:DWORD
	v_and_b32_sdwa v10, v107, v1 dst_sel:DWORD dst_unused:UNUSED_PAD src0_sel:WORD_1 src1_sel:DWORD
	v_add3_u32 v17, v99, v6, s26
	v_add3_u32 v19, v98, v7, s26
	v_add3_u32 v7, v107, v10, s26
	v_and_b32_e32 v6, 0xffff0000, v18
	v_and_b32_e32 v7, 0xffff0000, v7
	v_and_b32_e32 v16, 0xffff0000, v19
	v_and_b32_e32 v17, 0xffff0000, v17
	v_sub_f32_e32 v108, v132, v144
	v_or_b32_sdwa v15, v11, v15 dst_sel:DWORD dst_unused:UNUSED_PAD src0_sel:DWORD src1_sel:WORD_1
	v_pk_add_f32 v[10:11], v[106:107], v[6:7] neg_lo:[0,1] neg_hi:[0,1]
	v_pk_add_f32 v[96:97], v[98:99], v[16:17] neg_lo:[0,1] neg_hi:[0,1]
	v_or_b32_sdwa v16, v18, v7 dst_sel:DWORD dst_unused:UNUSED_PAD src0_sel:WORD_1 src1_sel:DWORD
	v_sub_f32_e32 v101, v137, v147
	v_sub_f32_e32 v100, v136, v146
	v_sub_f32_e32 v109, v134, v145
	v_and_b32_sdwa v7, v108, v1 dst_sel:DWORD dst_unused:UNUSED_PAD src0_sel:WORD_1 src1_sel:DWORD
	v_cvt_pk_bf16_f32 v18, v8, v9
	v_cvt_pk_bf16_f32 v20, v10, v11
	v_cvt_pk_bf16_f32 v21, v96, v97
	v_and_b32_sdwa v6, v101, v1 dst_sel:DWORD dst_unused:UNUSED_PAD src0_sel:WORD_1 src1_sel:DWORD
	v_add3_u32 v10, v108, v7, s26
	v_and_b32_sdwa v7, v100, v1 dst_sel:DWORD dst_unused:UNUSED_PAD src0_sel:WORD_1 src1_sel:DWORD
	v_and_b32_sdwa v8, v109, v1 dst_sel:DWORD dst_unused:UNUSED_PAD src0_sel:WORD_1 src1_sel:DWORD
	v_sub_f32_e32 v97, v126, v5
	v_sub_f32_e32 v104, v120, v2
	v_add3_u32 v9, v101, v6, s26
	v_add3_u32 v11, v100, v7, s26
	v_add3_u32 v7, v109, v8, s26
	v_sub_f32_e32 v96, v125, v4
	v_sub_f32_e32 v105, v123, v3
	v_and_b32_sdwa v2, v97, v1 dst_sel:DWORD dst_unused:UNUSED_PAD src0_sel:WORD_1 src1_sel:DWORD
	v_and_b32_sdwa v3, v104, v1 dst_sel:DWORD dst_unused:UNUSED_PAD src0_sel:WORD_1 src1_sel:DWORD
	v_and_b32_e32 v6, 0xffff0000, v10
	v_and_b32_e32 v7, 0xffff0000, v7
	v_and_b32_e32 v8, 0xffff0000, v11
	v_and_b32_e32 v9, 0xffff0000, v9
	v_add3_u32 v4, v97, v2, s26
	v_add3_u32 v120, v104, v3, s26
	v_and_b32_sdwa v3, v96, v1 dst_sel:DWORD dst_unused:UNUSED_PAD src0_sel:WORD_1 src1_sel:DWORD
	v_and_b32_sdwa v5, v105, v1 dst_sel:DWORD dst_unused:UNUSED_PAD src0_sel:WORD_1 src1_sel:DWORD
	v_or_b32_sdwa v17, v17, v19 dst_sel:DWORD dst_unused:UNUSED_PAD src0_sel:DWORD src1_sel:WORD_1
	v_cvt_pk_bf16_f32 v19, v12, v13
	v_pk_add_f32 v[12:13], v[108:109], v[6:7] neg_lo:[0,1] neg_hi:[0,1]
	v_pk_add_f32 v[140:141], v[100:101], v[8:9] neg_lo:[0,1] neg_hi:[0,1]
	v_or_b32_sdwa v137, v9, v11 dst_sel:DWORD dst_unused:UNUSED_PAD src0_sel:DWORD src1_sel:WORD_1
	v_or_b32_sdwa v136, v10, v7 dst_sel:DWORD dst_unused:UNUSED_PAD src0_sel:WORD_1 src1_sel:DWORD
	v_add3_u32 v123, v96, v3, s26
	v_add3_u32 v3, v105, v5, s26
	v_and_b32_e32 v139, 0xffff0000, v4
	ds_read2st64_b64 v[4:7], v184 offset0:32 offset1:36
	ds_read2st64_b64 v[8:11], v185 offset0:32 offset1:36
	v_and_b32_e32 v2, 0xffff0000, v120
	v_and_b32_e32 v3, 0xffff0000, v3
	v_and_b32_e32 v138, 0xffff0000, v123
	v_pk_add_f32 v[162:163], v[104:105], v[2:3] neg_lo:[0,1] neg_hi:[0,1]
	v_pk_add_f32 v[176:177], v[96:97], v[138:139] neg_lo:[0,1] neg_hi:[0,1]
	v_or_b32_sdwa v138, v120, v3 dst_sel:DWORD dst_unused:UNUSED_PAD src0_sel:WORD_1 src1_sel:DWORD
	s_waitcnt lgkmcnt(1)
	v_mov_b32_e32 v2, v4
	v_mov_b32_e32 v3, v5
	s_waitcnt lgkmcnt(0)
	v_mov_b32_e32 v4, v8
	v_mov_b32_e32 v5, v9
	ds_read2st64_b64 v[144:147], v184 offset0:48 offset1:52
	v_pk_mul_f32 v[148:149], v[94:95], v[60:61] op_sel_hi:[0,1]
	ds_read2st64_b64 v[152:155], v185 offset0:48 offset1:52
	v_pk_mul_f32 v[150:151], v[94:95], v[58:59] op_sel_hi:[0,1]
	ds_read2st64_b64 v[164:167], v187 offset0:32 offset1:36
	s_waitcnt lgkmcnt(2)
	v_mov_b32_e32 v156, v144
	v_mfma_f32_16x16x32_bf16 v[148:151], v[2:5], v[14:17], v[148:151]
	v_mov_b32_e32 v157, v145
	s_waitcnt lgkmcnt(1)
	v_mov_b32_e32 v158, v152
	v_mov_b32_e32 v159, v153
	v_mfma_f32_16x16x32_bf16 v[2:5], v[2:5], v[18:21], v[148:151]
	v_or_b32_sdwa v139, v139, v123 dst_sel:DWORD dst_unused:UNUSED_PAD src0_sel:DWORD src1_sel:WORD_1
	v_mov_b32_e32 v8, v6
	v_mov_b32_e32 v9, v7
	ds_read2st64_b64 v[148:151], v186 offset0:32 offset1:36
	v_mfma_f32_16x16x32_bf16 v[2:5], v[156:159], v[14:17], v[2:5]
	s_waitcnt lgkmcnt(1)
	v_mov_b32_e32 v158, v164
	v_mov_b32_e32 v159, v165
	v_cvt_pk_bf16_f32 v160, v12, v13
	s_waitcnt lgkmcnt(0)
	v_mov_b32_e32 v156, v148
	v_mov_b32_e32 v157, v149
	v_cvt_pk_bf16_f32 v161, v140, v141
	v_cvt_pk_bf16_f32 v162, v162, v163
	v_mfma_f32_16x16x32_bf16 v[2:5], v[156:159], v[136:139], v[2:5]
	v_cvt_pk_bf16_f32 v163, v176, v177
	v_mov_b32_e32 v152, v146
	v_mov_b32_e32 v153, v147
	v_mfma_f32_16x16x32_bf16 v[2:5], v[156:159], v[160:163], v[2:5]
	v_mul_f32_e64 v156, v94, v62
	v_mul_f32_e64 v157, v94, v63
	v_pk_mul_f32 v[158:159], v[94:95], v[64:65] op_sel_hi:[0,1]
	ds_read2st64_b64 v[168:171], v186 offset0:48 offset1:52
	ds_read2st64_b64 v[172:175], v187 offset0:48 offset1:52
	v_mfma_f32_16x16x32_bf16 v[156:159], v[8:11], v[14:17], v[156:159]
	v_mov_b32_e32 v164, v150
	v_mov_b32_e32 v165, v151
	ds_read2st64_b64 v[144:147], v184 offset0:40 offset1:44
	ds_read2st64_b64 v[148:151], v185 offset0:40 offset1:44
	v_mfma_f32_16x16x32_bf16 v[6:9], v[8:11], v[18:21], v[156:159]
	s_waitcnt lgkmcnt(2)
	v_mov_b32_e32 v178, v172
	v_mov_b32_e32 v179, v173
	s_waitcnt lgkmcnt(1)
	v_mov_b32_e32 v10, v144
	v_mfma_f32_16x16x32_bf16 v[6:9], v[152:155], v[14:17], v[6:9]
	v_mov_b32_e32 v11, v145
	s_waitcnt lgkmcnt(0)
	v_mov_b32_e32 v12, v148
	v_mov_b32_e32 v13, v149
	v_mfma_f32_16x16x32_bf16 v[6:9], v[164:167], v[136:139], v[6:9]
	v_mov_b32_e32 v148, v146
	v_mov_b32_e32 v149, v147
	v_mov_b32_e32 v172, v170
	v_mov_b32_e32 v173, v171
	v_mfma_f32_16x16x32_bf16 v[6:9], v[164:167], v[160:163], v[6:9]
	ds_read2st64_b64 v[152:155], v184 offset0:56 offset1:60
	v_pk_mul_f32 v[156:157], v[94:95], v[66:67] op_sel_hi:[0,1]
	ds_read2st64_b64 v[164:167], v185 offset0:56 offset1:60
	v_pk_mul_f32 v[158:159], v[94:95], v[68:69] op_sel_hi:[0,1]
	v_pk_mul_f32 v[144:145], v[94:95], v[70:71] op_sel_hi:[0,1]
	v_pk_mul_f32 v[146:147], v[94:95], v[72:73] op_sel_hi:[0,1]
	v_mfma_f32_16x16x32_bf16 v[156:159], v[10:13], v[14:17], v[156:159]
	v_mov_b32_e32 v176, v168
	v_mov_b32_e32 v177, v169
	s_waitcnt lgkmcnt(1)
	v_mov_b32_e32 v168, v152
	v_mfma_f32_16x16x32_bf16 v[144:147], v[148:151], v[14:17], v[144:147]
	v_mov_b32_e32 v169, v153
	s_waitcnt lgkmcnt(0)
	v_mov_b32_e32 v170, v164
	v_mov_b32_e32 v171, v165
	v_mfma_f32_16x16x32_bf16 v[6:9], v[172:175], v[136:139], v[6:9]
	v_mov_b32_e32 v164, v154
	v_mov_b32_e32 v165, v155
	v_mfma_f32_16x16x32_bf16 v[10:13], v[10:13], v[18:21], v[156:159]
	s_nop 2
	ds_read2st64_b64 v[156:159], v186 offset0:40 offset1:44
	ds_read2st64_b64 v[172:175], v187 offset0:40 offset1:44
	v_mfma_f32_16x16x32_bf16 v[18:21], v[148:151], v[18:21], v[144:147]
	v_mfma_f32_16x16x32_bf16 v[10:13], v[168:171], v[14:17], v[10:13]
	s_waitcnt lgkmcnt(1)
	v_mov_b32_e32 v168, v156
	v_mov_b32_e32 v169, v157
	s_waitcnt lgkmcnt(0)
	v_mov_b32_e32 v170, v172
	v_mov_b32_e32 v171, v173
	v_mov_b32_e32 v172, v158
	v_mov_b32_e32 v173, v159
	v_mfma_f32_16x16x32_bf16 v[14:17], v[164:167], v[14:17], v[18:21]
	v_mfma_f32_16x16x32_bf16 v[2:5], v[176:179], v[136:139], v[2:5]
	ds_read2st64_b64 v[176:179], v186 offset0:56 offset1:60
	ds_read2st64_b64 v[180:183], v187 offset0:56 offset1:60
	s_waitcnt vmcnt(0)
	s_waitcnt lgkmcnt(0)
	v_mfma_f32_16x16x32_bf16 v[10:13], v[168:171], v[136:139], v[10:13]
	v_mov_b32_e32 v184, v176
	v_mov_b32_e32 v185, v177
	v_mov_b32_e32 v186, v180
	v_mfma_f32_16x16x32_bf16 v[14:17], v[172:175], v[136:139], v[14:17]
	v_mov_b32_e32 v187, v181
	v_mov_b32_e32 v180, v178
	v_mov_b32_e32 v181, v179
	v_mfma_f32_16x16x32_bf16 v[10:13], v[168:171], v[160:163], v[10:13]
	s_barrier
	v_mfma_f32_16x16x32_bf16 v[14:17], v[172:175], v[160:163], v[14:17]
	v_mfma_f32_16x16x32_bf16 v[10:13], v[184:187], v[136:139], v[10:13]
	v_mfma_f32_16x16x32_bf16 v[14:17], v[180:183], v[136:139], v[14:17]
	s_cbranch_scc1 .LBB0_229
	v_mov_b32_e32 v94, v143
	s_mov_b32 s45, s43
	v_mov_b32_e32 v159, v60
	v_mov_b32_e32 v158, v61
	v_mov_b32_e32 v157, v58
	v_mov_b32_e32 v156, v59
	v_mov_b32_e32 v155, v62
	v_mov_b32_e32 v154, v63
	v_mov_b32_e32 v153, v64
	v_mov_b32_e32 v152, v65
	v_mov_b32_e32 v151, v66
	v_mov_b32_e32 v150, v67
	v_mov_b32_e32 v149, v68
	v_mov_b32_e32 v148, v69
	v_mov_b32_e32 v147, v70
	v_mov_b32_e32 v146, v71
	v_mov_b32_e32 v145, v72
	v_mov_b32_e32 v144, v73
	v_mov_b32_e32 v138, v113
	v_mov_b32_e32 v139, v114
	v_mov_b32_e32 v140, v115
	v_mov_b32_e32 v141, v116
	v_mov_b32_e32 v18, v117
	v_mov_b32_e32 v19, v118
	v_mov_b32_e32 v20, v119
	v_mov_b32_e32 v21, v121
	v_mov_b32_e32 v132, v122
	v_mov_b32_e32 v134, v124
	v_mov_b32_e32 v136, v127
	v_mov_b32_e32 v137, v128
	v_mov_b32_e32 v120, v129
	v_mov_b32_e32 v123, v133
	v_mov_b32_e32 v125, v135
	v_mov_b32_e32 v126, v142
	v_mov_b32_e32 v60, v2
	v_mov_b32_e32 v61, v3
	v_mov_b32_e32 v58, v4
	v_mov_b32_e32 v59, v5
	v_mov_b32_e32 v62, v6
	v_mov_b32_e32 v63, v7
	v_mov_b32_e32 v64, v8
	v_mov_b32_e32 v65, v9
	v_mov_b32_e32 v66, v10
	v_mov_b32_e32 v67, v11
	v_mov_b32_e32 v68, v12
	v_mov_b32_e32 v69, v13
	v_mov_b32_e32 v70, v14
	v_mov_b32_e32 v71, v15
	v_mov_b32_e32 v72, v16
	v_mov_b32_e32 v73, v17
	s_branch .LBB0_223
